# one static s_setprio 1 for waves 0-3 through the attention phase (per-half comparison of the static priority raise)
# speedup vs baseline: 1.0023x; 1.0023x over previous
; #define KA_BEGIN() kargp_t KA = (kargp_t)__builtin_amdgcn_kernarg_segment_ptr(); asm volatile("" : "+s"(KA)); unsigned char* const ws = (unsigned char*)(GAS unsigned char*)KA[29]; float* const out = (float*)(GAS float*)KA[28]; (void)ws; (void)out
; #define TIDS() int tid = threadIdx.x; asm volatile("" : "+v"(tid)); const int lane = tid & 63, wave = __builtin_amdgcn_readfirstlane(tid >> 6); const int gw = bid * NWAVES + wave, NGW = G * NWAVES; (void)lane; (void)gw; (void)NGW
; __global__ void __launch_bounds__(NTHR, 2) fwd_kernel(Args args) {
;     ...
;     if (PH(3)) { KA_BEGIN(); TIDS();
;         unsigned* ctl = (unsigned*)(ws + WS_CTL);
;     ...
;         if (bid < 4) { const float *PE = (const float*)(ws + WS_PE), *LE = (const float*)(ws + WS_LE); float* HIN = (float*)(ws + WS_HIN); const int chn = bid * NTHR + tid; float H = 0.f;
.LBB0_1270:
	s_or_b64 exec, exec, s[6:7]
	s_mov_b64 s[20:21], s[96:97]
	s_waitcnt lgkmcnt(0)
	s_barrier
	v_readfirstlane_b32 s98, v0
	s_nop 3
	s_lshr_b32 s98, s98, 6
	s_cmp_lt_u32 s98, 4
	s_cbranch_scc0 .Lp3prio_done
	s_setprio 1
